# attention loop: third V-fragment buffer so the last group's LDS reads issue one group earlier; barriers moved one group earlier for both halves (A before group 6, B before group 5), B waits vmcnt only
# baseline (speedup 1.0000x reference)
; #define LAS __attribute__((address_space(3)))
; #define ATT_VTR(p) __builtin_bit_cast(s16x4, __builtin_amdgcn_ds_read_tr16_b64_v4i16((LAS s16x4*)(p)))
; DI void attn_unit(LAS unsigned char* lds, const bf16_t* P, bf16_t* Am, int qrow0, int h, int ntiles, int krow_ctx, int krow_lat,
;                   float lam, const float* subw, float outscale) {
;     ...
;     int s0 = 0, s1 = 1, s2 = 2;
;     for (int t = 0; t < ntiles; ++t) {
;         const bool more = (t + 2 < ntiles);
;         if (more) ATT_DMA_KV(t + 2, s2);
;         LAS unsigned char* kp = lds + s0 * 16384 + kb_off;
;         LAS unsigned char* vp0 = lds + s0 * 16384 + vb_par[0];
;         LAS unsigned char* vp1 = lds + s0 * 16384 + vb_par[1];
;         u32x4 pwa[4], pwb[4];
;     ...
;         ATT_QKP(ATT_QA, lsa, pwa);
;         ATT_QKP(ATT_QB, lsb, pwb);
;     ...
;         {
;             s16x4 vl[2][2], vh[2][2];
; #pragma unroll
;             for (int i = 0; i < 2; ++i) { LAS unsigned char* vq = (i ? vp1 : vp0); vl[0][i] = ATT_VTR(vq); vh[0][i] = ATT_VTR(vq + 1024); }
; #pragma unroll
;             for (int gi = 0; gi < 8; ++gi) { const int ks = gi >> 1, dp = gi & 1;
;                 if (gi < 7) { const int ks2 = (gi + 1) >> 1, dp2 = (gi + 1) & 1;
; #pragma unroll
;                     for (int i = 0; i < 2; ++i) { LAS unsigned char* vq = (i ? vp1 : vp0) + dp2 * 8192 + ks2 * 2048; vl[(gi + 1) & 1][i] = ATT_VTR(vq); vh[(gi + 1) & 1][i] = ATT_VTR(vq + 1024); } }
.LBB0_333:
	s_lshl_b32 s0, s5, 14
	s_add_i32 s6, s0, s63
	v_add_u32_e32 v236, s6, v244
	v_add_u32_e32 v232, v236, v222
	ds_read_b128 v[176:179], v232
	v_add_u32_e32 v233, v236, v241
	ds_read_b128 v[180:183], v233
	v_add_u32_e32 v234, v236, v240
	ds_read_b128 v[184:187], v234
	v_add_u32_e32 v235, v236, v248
	ds_read_b128 v[188:191], v235
	ds_read_b128 v[224:227], v253
	ds_read_b128 v[228:231], v253 offset:1024
	ds_read_b128 v[168:171], v253 offset:2048
	ds_read_b128 v[160:163], v253 offset:3072
	v_add_u32_e32 v218, s0, v249
	v_add_u32_e32 v243, s0, v245
	s_add_i32 s4, s4, 1
	s_add_i32 s58, s58, 64
	s_waitcnt lgkmcnt(7)
	v_mfma_f32_32x32x16_bf16 v[128:143], v[176:179], v[144:147], 0
	s_waitcnt lgkmcnt(6)
	v_mfma_f32_32x32x16_bf16 v[128:143], v[180:183], v[148:151], v[128:143]
	s_waitcnt lgkmcnt(5)
	v_mfma_f32_32x32x16_bf16 v[128:143], v[184:187], v[152:155], v[128:143]
	s_waitcnt lgkmcnt(4)
	v_mfma_f32_32x32x16_bf16 v[128:143], v[188:191], v[156:159], v[128:143]
	s_waitcnt lgkmcnt(3)
	v_mfma_f32_32x32x16_bf16 v[192:207], v[176:179], v[224:227], 0
	s_waitcnt lgkmcnt(2)
	v_mfma_f32_32x32x16_bf16 v[192:207], v[180:183], v[228:231], v[192:207]
	s_waitcnt lgkmcnt(1)
	v_mfma_f32_32x32x16_bf16 v[192:207], v[184:187], v[168:171], v[192:207]
	s_waitcnt lgkmcnt(0)
	v_mfma_f32_32x32x16_bf16 v[192:207], v[188:191], v[160:163], v[192:207]
	ds_read_b128 v[176:179], v232 offset:4096
	ds_read_b128 v[180:183], v233 offset:4096
	ds_read_b128 v[184:187], v234 offset:4096
	ds_read_b128 v[188:191], v235 offset:4096
	v_exp_f32_e32 v128, v128
	v_exp_f32_e32 v129, v129
	v_exp_f32_e32 v130, v130
	v_exp_f32_e32 v131, v131
	v_add_f32_e32 v164, v128, v130
	v_add_f32_e32 v165, v129, v131
	v_exp_f32_e32 v132, v132
	v_exp_f32_e32 v133, v133
	v_add_f32_e32 v164, v164, v132
	v_add_f32_e32 v165, v165, v133
	v_exp_f32_e32 v134, v134
	v_exp_f32_e32 v135, v135
	v_add_f32_e32 v164, v164, v134
	v_add_f32_e32 v165, v165, v135
	v_exp_f32_e32 v136, v136
	v_exp_f32_e32 v137, v137
	v_add_f32_e32 v164, v164, v136
	v_add_f32_e32 v165, v165, v137
	v_exp_f32_e32 v138, v138
	v_exp_f32_e32 v139, v139
	v_add_f32_e32 v164, v164, v138
	v_add_f32_e32 v165, v165, v139
	v_exp_f32_e32 v140, v140
	v_exp_f32_e32 v141, v141
	v_add_f32_e32 v164, v164, v140
	v_add_f32_e32 v165, v165, v141
	v_exp_f32_e32 v142, v142
	v_exp_f32_e32 v143, v143
	v_add_f32_e32 v210, v164, v142
	v_add_f32_e32 v212, v165, v143
	v_cvt_pk_bf16_f32 v172, v128, v129
	v_cvt_pk_bf16_f32 v173, v130, v131
	v_cvt_pk_bf16_f32 v174, v132, v133
	v_cvt_pk_bf16_f32 v175, v134, v135
	v_cvt_pk_bf16_f32 v164, v136, v137
	v_cvt_pk_bf16_f32 v165, v138, v139
	v_cvt_pk_bf16_f32 v166, v140, v141
	v_cvt_pk_bf16_f32 v167, v142, v143
	s_waitcnt lgkmcnt(3)
	v_mfma_f32_32x32x16_bf16 v[128:143], v[176:179], v[144:147], 0
	v_exp_f32_e32 v192, v192
	v_exp_f32_e32 v193, v193
	v_exp_f32_e32 v194, v194
	v_exp_f32_e32 v195, v195
	v_add_f32_e32 v236, v192, v194
	v_add_f32_e32 v237, v193, v195
	s_waitcnt lgkmcnt(2)
	v_mfma_f32_32x32x16_bf16 v[128:143], v[180:183], v[148:151], v[128:143]
	v_exp_f32_e32 v196, v196
	v_exp_f32_e32 v197, v197
	v_add_f32_e32 v236, v236, v196
	v_add_f32_e32 v237, v237, v197
	v_exp_f32_e32 v198, v198
	v_exp_f32_e32 v199, v199
	s_waitcnt lgkmcnt(1)
	v_mfma_f32_32x32x16_bf16 v[128:143], v[184:187], v[152:155], v[128:143]
	v_add_f32_e32 v236, v236, v198
	v_add_f32_e32 v237, v237, v199
	v_exp_f32_e32 v200, v200
	v_exp_f32_e32 v201, v201
	v_add_f32_e32 v236, v236, v200
	v_add_f32_e32 v237, v237, v201
	s_waitcnt lgkmcnt(0)
	v_mfma_f32_32x32x16_bf16 v[128:143], v[188:191], v[156:159], v[128:143]
	v_exp_f32_e32 v202, v202
	v_exp_f32_e32 v203, v203
	v_add_f32_e32 v236, v236, v202
	v_add_f32_e32 v237, v237, v203
	v_exp_f32_e32 v204, v204
	v_exp_f32_e32 v205, v205
	v_add_f32_e32 v236, v236, v204
	v_add_f32_e32 v237, v237, v205
	v_exp_f32_e32 v206, v206
	v_exp_f32_e32 v207, v207
	v_add_f32_e32 v211, v236, v206
	v_add_f32_e32 v213, v237, v207
	v_cvt_pk_bf16_f32 v232, v192, v193
	v_cvt_pk_bf16_f32 v233, v194, v195
	v_cvt_pk_bf16_f32 v234, v196, v197
	v_cvt_pk_bf16_f32 v235, v198, v199
	v_cvt_pk_bf16_f32 v236, v200, v201
	v_cvt_pk_bf16_f32 v237, v202, v203
	v_cvt_pk_bf16_f32 v238, v204, v205
	v_cvt_pk_bf16_f32 v239, v206, v207
	v_mfma_f32_32x32x16_bf16 v[192:207], v[176:179], v[224:227], 0
	v_exp_f32_e32 v128, v128
	v_exp_f32_e32 v129, v129
	v_exp_f32_e32 v130, v130
	v_exp_f32_e32 v131, v131
	v_add_f32_e32 v224, v128, v130
	v_add_f32_e32 v225, v129, v131
	v_mfma_f32_32x32x16_bf16 v[192:207], v[180:183], v[228:231], v[192:207]
	v_exp_f32_e32 v132, v132
	v_exp_f32_e32 v133, v133
	v_add_f32_e32 v224, v224, v132
	v_add_f32_e32 v225, v225, v133
	v_exp_f32_e32 v134, v134
	v_exp_f32_e32 v135, v135
	v_mfma_f32_32x32x16_bf16 v[192:207], v[184:187], v[168:171], v[192:207]
	v_add_f32_e32 v224, v224, v134
	v_add_f32_e32 v225, v225, v135
	v_exp_f32_e32 v136, v136
	v_exp_f32_e32 v137, v137
	v_add_f32_e32 v224, v224, v136
	v_add_f32_e32 v225, v225, v137
	v_mfma_f32_32x32x16_bf16 v[192:207], v[188:191], v[160:163], v[192:207]
	v_exp_f32_e32 v138, v138
	v_exp_f32_e32 v139, v139
	v_add_f32_e32 v224, v224, v138
	v_add_f32_e32 v225, v225, v139
	ds_read_b64_tr_b16 v[176:177], v218 offset:49152
	ds_read_b64_tr_b16 v[178:179], v218 offset:50176
	ds_read_b64_tr_b16 v[180:181], v243 offset:49152
	ds_read_b64_tr_b16 v[182:183], v243 offset:50176
	v_exp_f32_e32 v140, v140
	v_exp_f32_e32 v141, v141
	v_add_f32_e32 v224, v224, v140
	v_add_f32_e32 v225, v225, v141
	ds_read_b64_tr_b16 v[184:185], v218 offset:57344
	ds_read_b64_tr_b16 v[186:187], v218 offset:58368
	ds_read_b64_tr_b16 v[188:189], v243 offset:57344
	ds_read_b64_tr_b16 v[190:191], v243 offset:58368
	v_exp_f32_e32 v142, v142
	v_exp_f32_e32 v143, v143
	v_add_f32_e32 v214, v224, v142
	v_add_f32_e32 v216, v225, v143
	v_cvt_pk_bf16_f32 v168, v128, v129
	v_cvt_pk_bf16_f32 v169, v130, v131
	v_cvt_pk_bf16_f32 v170, v132, v133
	v_cvt_pk_bf16_f32 v171, v134, v135
	v_cvt_pk_bf16_f32 v160, v136, v137
	v_cvt_pk_bf16_f32 v161, v138, v139
	v_cvt_pk_bf16_f32 v162, v140, v141
	v_cvt_pk_bf16_f32 v163, v142, v143
	v_exp_f32_e32 v192, v192
	s_waitcnt lgkmcnt(6)
; #define LAS __attribute__((address_space(3)))
; #define ATT_WAIT_BAR() asm volatile("s_waitcnt vmcnt(0) lgkmcnt(0)\n\ts_barrier" ::: "memory")
; #define ATT_VTR(p) __builtin_bit_cast(s16x4, __builtin_amdgcn_ds_read_tr16_b64_v4i16((LAS s16x4*)(p)))
; DI void attn_unit(LAS unsigned char* lds, const bf16_t* P, bf16_t* Am, int qrow0, int h, int ntiles, int krow_ctx, int krow_lat,
;                   float lam, const float* subw, float outscale) {
;     ...
;             for (int i = 0; i < 2; ++i) { LAS unsigned char* vq = (i ? vp1 : vp0); vl[0][i] = ATT_VTR(vq); vh[0][i] = ATT_VTR(vq + 1024); }
; #pragma unroll
;             for (int gi = 0; gi < 8; ++gi) { const int ks = gi >> 1, dp = gi & 1;
;                 if (gi < 7) { const int ks2 = (gi + 1) >> 1, dp2 = (gi + 1) & 1;
; #pragma unroll
;                     for (int i = 0; i < 2; ++i) { LAS unsigned char* vq = (i ? vp1 : vp0) + dp2 * 8192 + ks2 * 2048; vl[(gi + 1) & 1][i] = ATT_VTR(vq); vh[(gi + 1) & 1][i] = ATT_VTR(vq + 1024); } }
;                 __builtin_amdgcn_sched_barrier(0x406);
; #pragma unroll
;                 for (int i = 0; i < 2; ++i) { const int d0 = 2 * dp + i; const s16x4 lo = vl[gi & 1][i], hh = vh[gi & 1][i];
;                     const bf16x8 vf = {lo[0], lo[1], lo[2], lo[3], hh[0], hh[1], hh[2], hh[3]};
;                     oa[d0] = __builtin_amdgcn_mfma_f32_32x32x16_bf16(vf, __builtin_bit_cast(bf16x8, pwa[ks]), oa[d0], 0, 0, 0);
;                     ob[d0] = __builtin_amdgcn_mfma_f32_32x32x16_bf16(vf, __builtin_bit_cast(bf16x8, pwb[ks]), ob[d0], 0, 0, 0); }
;                 __builtin_amdgcn_sched_barrier(0x406);
;             }
;         }
;         ATT_WAIT_BAR();
	v_mfma_f32_32x32x16_bf16 v[112:127], v[176:179], v[172:175], v[112:127]
	v_exp_f32_e32 v193, v193
	v_exp_f32_e32 v194, v194
	v_mfma_f32_32x32x16_bf16 v[48:63], v[176:179], v[232:235], v[48:63]
	v_exp_f32_e32 v195, v195
	v_add_f32_e32 v128, v192, v194
	s_waitcnt lgkmcnt(4)
	v_mfma_f32_32x32x16_bf16 v[96:111], v[180:183], v[172:175], v[96:111]
	v_add_f32_e32 v129, v193, v195
	v_exp_f32_e32 v196, v196
	v_mfma_f32_32x32x16_bf16 v[32:47], v[180:183], v[232:235], v[32:47]
	v_exp_f32_e32 v197, v197
	ds_read_b64_tr_b16 v[176:177], v218 offset:51200
	ds_read_b64_tr_b16 v[178:179], v218 offset:52224
	ds_read_b64_tr_b16 v[180:181], v243 offset:51200
	ds_read_b64_tr_b16 v[182:183], v243 offset:52224
	v_add_f32_e32 v128, v128, v196
	v_add_f32_e32 v129, v129, v197
	s_waitcnt lgkmcnt(6)
	v_mfma_f32_32x32x16_bf16 v[80:95], v[184:187], v[172:175], v[80:95]
	v_exp_f32_e32 v198, v198
	v_exp_f32_e32 v199, v199
	v_mfma_f32_32x32x16_bf16 v[16:31], v[184:187], v[232:235], v[16:31]
	v_add_f32_e32 v128, v128, v198
	v_add_f32_e32 v129, v129, v199
	s_waitcnt lgkmcnt(4)
	v_mfma_f32_32x32x16_bf16 v[64:79], v[188:191], v[172:175], v[64:79]
	v_exp_f32_e32 v200, v200
	v_exp_f32_e32 v201, v201
	v_mfma_f32_32x32x16_bf16 v[0:15], v[188:191], v[232:235], v[0:15]
	v_add_f32_e32 v128, v128, v200
	ds_read_b64_tr_b16 v[184:185], v218 offset:59392
	ds_read_b64_tr_b16 v[186:187], v218 offset:60416
	ds_read_b64_tr_b16 v[188:189], v243 offset:59392
	ds_read_b64_tr_b16 v[190:191], v243 offset:60416
	v_add_f32_e32 v129, v129, v201
	v_exp_f32_e32 v202, v202
	s_waitcnt lgkmcnt(6)
	v_mfma_f32_32x32x16_bf16 v[112:127], v[176:179], v[164:167], v[112:127]
	v_exp_f32_e32 v203, v203
	v_add_f32_e32 v128, v128, v202
	v_mfma_f32_32x32x16_bf16 v[48:63], v[176:179], v[236:239], v[48:63]
	v_add_f32_e32 v129, v129, v203
	v_exp_f32_e32 v204, v204
	s_waitcnt lgkmcnt(4)
	v_mfma_f32_32x32x16_bf16 v[96:111], v[180:183], v[164:167], v[96:111]
	v_exp_f32_e32 v205, v205
	v_add_f32_e32 v128, v128, v204
	v_mfma_f32_32x32x16_bf16 v[32:47], v[180:183], v[236:239], v[32:47]
	v_add_f32_e32 v129, v129, v205
	ds_read_b64_tr_b16 v[176:177], v218 offset:53248
	ds_read_b64_tr_b16 v[178:179], v218 offset:54272
	ds_read_b64_tr_b16 v[180:181], v243 offset:53248
	ds_read_b64_tr_b16 v[182:183], v243 offset:54272
	v_exp_f32_e32 v206, v206
	v_exp_f32_e32 v207, v207
	s_waitcnt lgkmcnt(6)
	v_mfma_f32_32x32x16_bf16 v[80:95], v[184:187], v[164:167], v[80:95]
	v_add_f32_e32 v215, v128, v206
	v_add_f32_e32 v217, v129, v207
	v_mfma_f32_32x32x16_bf16 v[16:31], v[184:187], v[236:239], v[16:31]
	v_cvt_pk_bf16_f32 v132, v192, v193
	v_cvt_pk_bf16_f32 v133, v194, v195
	s_waitcnt lgkmcnt(4)
	v_mfma_f32_32x32x16_bf16 v[64:79], v[188:191], v[164:167], v[64:79]
	v_cvt_pk_bf16_f32 v134, v196, v197
	v_cvt_pk_bf16_f32 v135, v198, v199
	v_mfma_f32_32x32x16_bf16 v[0:15], v[188:191], v[236:239], v[0:15]
	v_cvt_pk_bf16_f32 v128, v200, v201
	ds_read_b64_tr_b16 v[184:185], v218 offset:61440
	ds_read_b64_tr_b16 v[186:187], v218 offset:62464
	ds_read_b64_tr_b16 v[188:189], v243 offset:61440
	ds_read_b64_tr_b16 v[190:191], v243 offset:62464
	v_cvt_pk_bf16_f32 v129, v202, v203
	v_cvt_pk_bf16_f32 v130, v204, v205
	v_cvt_pk_bf16_f32 v131, v206, v207
	v_pk_add_f32 v[224:225], v[210:211], v[212:213]
	v_pk_add_f32 v[224:225], v[208:209], v[224:225]
	v_add_f32_e32 v226, v214, v216
	v_add_f32_e32 v227, v215, v217
	v_add_f32_e32 v208, v224, v226
	v_add_f32_e32 v209, v225, v227
	s_waitcnt lgkmcnt(6)
	v_mfma_f32_32x32x16_bf16 v[112:127], v[176:179], v[168:171], v[112:127]
	v_mfma_f32_32x32x16_bf16 v[48:63], v[176:179], v[132:135], v[48:63]
	s_waitcnt lgkmcnt(4)
	v_mfma_f32_32x32x16_bf16 v[96:111], v[180:183], v[168:171], v[96:111]
	v_mfma_f32_32x32x16_bf16 v[32:47], v[180:183], v[132:135], v[32:47]
	ds_read_b64_tr_b16 v[176:177], v218 offset:55296
	ds_read_b64_tr_b16 v[178:179], v218 offset:56320
	ds_read_b64_tr_b16 v[180:181], v243 offset:55296
	ds_read_b64_tr_b16 v[182:183], v243 offset:56320
	ds_read_b64_tr_b16 v[224:225], v218 offset:63488
	ds_read_b64_tr_b16 v[226:227], v218 offset:64512
	ds_read_b64_tr_b16 v[228:229], v243 offset:63488
	ds_read_b64_tr_b16 v[230:231], v243 offset:64512
	s_cmp_eq_u32 s38, 0
	s_cbranch_scc1 .Latt_midskip_l
	s_waitcnt vmcnt(0)
	s_barrier
	s_cmp_gt_u32 s4, s1
	s_cbranch_scc1 .Latt_midskip_l
	s_add_i32 s6, s58, 0xffffffc0
	s_mul_hi_i32 s7, s6, 0x3000
	s_mul_i32 s6, s6, 0x3000
	s_add_u32 s6, s50, s6
	s_addc_u32 s7, s51, s7
	s_add_u32 s8, s6, 0x80
	s_addc_u32 s9, s7, 0
	s_lshl_b32 s10, s60, 14
	s_mov_b32 s11, m0
	s_add_i32 s10, s10, s61
	s_mov_b32 m0, s10
	s_nop 0
	global_load_lds_dwordx4 v251, s[6:7]
	s_addk_i32 s10, 0x2000
	s_mov_b32 m0, s10
	s_nop 0
	global_load_lds_dwordx4 v251, s[8:9]
	s_add_i32 s10, s10, 0xa000
	s_mov_b32 m0, s10
	s_nop 0
	global_load_lds_dwordx4 v252, s[6:7]
	s_addk_i32 s10, 0x2000
	s_mov_b32 m0, s10
	s_nop 0
	global_load_lds_dwordx4 v252, s[8:9]
	s_mov_b32 m0, s11
.Latt_midskip_l:
	s_waitcnt lgkmcnt(10)
	v_mfma_f32_32x32x16_bf16 v[80:95], v[184:187], v[168:171], v[80:95]
	v_mfma_f32_32x32x16_bf16 v[16:31], v[184:187], v[132:135], v[16:31]
	s_waitcnt lgkmcnt(8)
	v_mfma_f32_32x32x16_bf16 v[64:79], v[188:191], v[168:171], v[64:79]
	v_mfma_f32_32x32x16_bf16 v[0:15], v[188:191], v[132:135], v[0:15]
	s_cmp_lg_u32 s38, 0
	s_cbranch_scc1 .Latt_endskip_l
	s_waitcnt vmcnt(0) lgkmcnt(0)
	s_barrier
; #define LAS __attribute__((address_space(3)))
; #define ATT_WAIT_BAR() asm volatile("s_waitcnt vmcnt(0) lgkmcnt(0)\n\ts_barrier" ::: "memory")
; DI void attn_unit(LAS unsigned char* lds, const bf16_t* P, bf16_t* Am, int qrow0, int h, int ntiles, int krow_ctx, int krow_lat,
;                   float lam, const float* subw, float outscale) {
;     ...
;                 for (int i = 0; i < 2; ++i) { const int d0 = 2 * dp + i; const s16x4 lo = vl[gi & 1][i], hh = vh[gi & 1][i];
;                     const bf16x8 vf = {lo[0], lo[1], lo[2], lo[3], hh[0], hh[1], hh[2], hh[3]};
;                     oa[d0] = __builtin_amdgcn_mfma_f32_32x32x16_bf16(vf, __builtin_bit_cast(bf16x8, pwa[ks]), oa[d0], 0, 0, 0);
;                     ob[d0] = __builtin_amdgcn_mfma_f32_32x32x16_bf16(vf, __builtin_bit_cast(bf16x8, pwb[ks]), ob[d0], 0, 0, 0); }
;                 __builtin_amdgcn_sched_barrier(0x406);
;             }
;         }
;         ATT_WAIT_BAR();
;         { const int tmp = s0; s0 = s1; s1 = s2; s2 = tmp; }
;     }
;     ...
;     lsa = sum_x32(lsa); lsb = sum_x32(lsb);
;     const float inva = 1.0f / lsa, invb = 1.0f / lsb;
;     int tid2 = threadIdx.x; asm volatile("" : "+v"(tid2));
;     const int lane2 = tid2 & 63, r32e = lane2 & 31, hie = lane2 >> 5;
;     LAS float* xch = (LAS float*)lds + g * 8192;
;     if (n == 1) { const float sa = inva * lam, sb = invb * lam;
; #pragma unroll
;         for (int d0 = 0; d0 < 4; ++d0)
; #pragma unroll
;             for (int r = 0; r < 16; ++r) { xch[(d0 * 16 + r) * 64 + lane2] = oa[d0][r] * sa; xch[4096 + (d0 * 16 + r) * 64 + lane2] = ob[d0][r] * sb; } }
.Latt_endskip_l:
	s_waitcnt lgkmcnt(6)
	v_mfma_f32_32x32x16_bf16 v[112:127], v[176:179], v[160:163], v[112:127]
	v_mfma_f32_32x32x16_bf16 v[48:63], v[176:179], v[128:131], v[48:63]
	s_waitcnt lgkmcnt(4)
	v_mfma_f32_32x32x16_bf16 v[96:111], v[180:183], v[160:163], v[96:111]
	v_mfma_f32_32x32x16_bf16 v[32:47], v[180:183], v[128:131], v[32:47]
	s_waitcnt lgkmcnt(2)
	v_mfma_f32_32x32x16_bf16 v[80:95], v[224:227], v[160:163], v[80:95]
	v_mfma_f32_32x32x16_bf16 v[16:31], v[224:227], v[128:131], v[16:31]
	s_waitcnt lgkmcnt(0)
	v_mfma_f32_32x32x16_bf16 v[64:79], v[228:231], v[160:163], v[64:79]
	v_mfma_f32_32x32x16_bf16 v[0:15], v[228:231], v[128:131], v[0:15]
	s_cmp_eq_u32 s59, s4
	s_cbranch_scc0 .LBB0_331
	v_mov_b32_e32 v128, v208
	s_nop 1
	v_permlane32_swap_b32_e32 v208, v128
	v_add_f32_e32 v128, v208, v128
	v_div_scale_f32 v130, s[0:1], v128, v128, 1.0
	v_rcp_f32_e32 v131, v130
	v_mov_b32_e32 v129, v209
	s_nop 1
	v_permlane32_swap_b32_e32 v209, v129
	v_fma_f32 v132, -v130, v131, 1.0
	v_fmac_f32_e32 v131, v132, v131
	v_div_scale_f32 v132, vcc, 1.0, v128, 1.0
	v_mul_f32_e32 v133, v132, v131
	v_fma_f32 v134, -v130, v133, v132
	v_fmac_f32_e32 v133, v134, v131
	v_fma_f32 v130, -v130, v133, v132
	v_add_f32_e32 v129, v209, v129
	v_div_fmas_f32 v130, v130, v131, v133
	v_div_fixup_f32 v138, v130, v128, 1.0
	v_div_scale_f32 v128, s[0:1], v129, v129, 1.0
	v_rcp_f32_e32 v130, v128
	s_lshl_b32 s0, s39, 15
	s_add_i32 s0, s0, 0
	s_cmp_eq_u32 s38, 1
	v_fma_f32 v131, -v128, v130, 1.0
	v_fmac_f32_e32 v130, v131, v130
	v_div_scale_f32 v131, vcc, 1.0, v129, 1.0
	v_mul_f32_e32 v132, v131, v130
	v_fma_f32 v133, -v128, v132, v131
	v_fmac_f32_e32 v132, v133, v130
	v_fma_f32 v128, -v128, v132, v131
	v_div_fmas_f32 v128, v128, v130, v132
	v_div_fixup_f32 v136, v128, v129, 1.0
	v_mov_b32_e32 v128, v220
	s_nop 0
	v_and_b32_e32 v129, 63, v128
	v_lshl_add_u32 v214, v129, 2, s0
	s_cbranch_scc0 .LBB0_336
	s_waitcnt vmcnt(0) lgkmcnt(0)
	s_barrier
	v_mul_f32_e32 v130, s19, v138
	v_mul_f32_e32 v131, s19, v136
	v_mul_f32_e32 v132, v112, v130
	v_mul_f32_e32 v134, v113, v130
	v_mul_f32_e32 v133, v48, v131
	ds_write2st64_b32 v214, v132, v134 offset1:1
	v_mul_f32_e32 v132, v49, v131
	ds_write2st64_b32 v214, v133, v132 offset0:64 offset1:65
	v_mul_f32_e32 v132, v114, v130
	v_mul_f32_e32 v134, v115, v130
	v_mul_f32_e32 v133, v50, v131
	ds_write2st64_b32 v214, v132, v134 offset0:2 offset1:3
	v_mul_f32_e32 v132, v51, v131
	ds_write2st64_b32 v214, v133, v132 offset0:66 offset1:67
	v_mul_f32_e32 v132, v116, v130
	v_mul_f32_e32 v134, v117, v130
	v_mul_f32_e32 v133, v52, v131
	ds_write2st64_b32 v214, v132, v134 offset0:4 offset1:5
	v_mul_f32_e32 v132, v53, v131
	ds_write2st64_b32 v214, v133, v132 offset0:68 offset1:69
	v_mul_f32_e32 v132, v118, v130
	v_mul_f32_e32 v134, v119, v130
	v_mul_f32_e32 v133, v54, v131
	ds_write2st64_b32 v214, v132, v134 offset0:6 offset1:7
	v_mul_f32_e32 v132, v55, v131
	ds_write2st64_b32 v214, v133, v132 offset0:70 offset1:71
	v_mul_f32_e32 v132, v120, v130
	v_mul_f32_e32 v134, v121, v130
	v_mul_f32_e32 v133, v56, v131
	ds_write2st64_b32 v214, v132, v134 offset0:8 offset1:9
	v_mul_f32_e32 v132, v57, v131
	ds_write2st64_b32 v214, v133, v132 offset0:72 offset1:73
	v_mul_f32_e32 v132, v122, v130
	v_mul_f32_e32 v134, v123, v130
	v_mul_f32_e32 v133, v58, v131
	ds_write2st64_b32 v214, v132, v134 offset0:10 offset1:11
	v_mul_f32_e32 v132, v59, v131
	ds_write2st64_b32 v214, v133, v132 offset0:74 offset1:75
	v_mul_f32_e32 v132, v124, v130
	v_mul_f32_e32 v134, v125, v130
	v_mul_f32_e32 v133, v60, v131
	ds_write2st64_b32 v214, v132, v134 offset0:12 offset1:13
	v_mul_f32_e32 v132, v61, v131
	ds_write2st64_b32 v214, v133, v132 offset0:76 offset1:77
	v_mul_f32_e32 v132, v126, v130
	v_mul_f32_e32 v134, v127, v130
	v_mul_f32_e32 v133, v62, v131
	ds_write2st64_b32 v214, v132, v134 offset0:14 offset1:15
	v_mul_f32_e32 v132, v63, v131
	ds_write2st64_b32 v214, v133, v132 offset0:78 offset1:79
	v_mul_f32_e32 v132, v96, v130
	v_mul_f32_e32 v134, v97, v130
	v_mul_f32_e32 v133, v32, v131
	ds_write2st64_b32 v214, v132, v134 offset0:16 offset1:17
	v_mul_f32_e32 v132, v33, v131
	ds_write2st64_b32 v214, v133, v132 offset0:80 offset1:81
	v_mul_f32_e32 v132, v98, v130
	v_mul_f32_e32 v134, v99, v130
	v_mul_f32_e32 v133, v34, v131
	ds_write2st64_b32 v214, v132, v134 offset0:18 offset1:19
	v_mul_f32_e32 v132, v35, v131
	ds_write2st64_b32 v214, v133, v132 offset0:82 offset1:83
	v_mul_f32_e32 v132, v100, v130
	v_mul_f32_e32 v134, v101, v130
	v_mul_f32_e32 v133, v36, v131
	ds_write2st64_b32 v214, v132, v134 offset0:20 offset1:21
	v_mul_f32_e32 v132, v37, v131
	ds_write2st64_b32 v214, v133, v132 offset0:84 offset1:85
	v_mul_f32_e32 v132, v102, v130
	v_mul_f32_e32 v134, v103, v130
	v_mul_f32_e32 v133, v38, v131
	ds_write2st64_b32 v214, v132, v134 offset0:22 offset1:23
	v_mul_f32_e32 v132, v39, v131
; DI void attn_unit(LAS unsigned char* lds, const bf16_t* P, bf16_t* Am, int qrow0, int h, int ntiles, int krow_ctx, int krow_lat,
;                   float lam, const float* subw, float outscale) {
;     ...
;     if (n == 1) { const float sa = inva * lam, sb = invb * lam;
; #pragma unroll
;         for (int d0 = 0; d0 < 4; ++d0)
; #pragma unroll
;             for (int r = 0; r < 16; ++r) { xch[(d0 * 16 + r) * 64 + lane2] = oa[d0][r] * sa; xch[4096 + (d0 * 16 + r) * 64 + lane2] = ob[d0][r] * sb; } }
	ds_write2st64_b32 v214, v133, v132 offset0:86 offset1:87
	v_mul_f32_e32 v132, v104, v130
	v_mul_f32_e32 v134, v105, v130
	v_mul_f32_e32 v133, v40, v131
	ds_write2st64_b32 v214, v132, v134 offset0:24 offset1:25
	v_mul_f32_e32 v132, v41, v131
	ds_write2st64_b32 v214, v133, v132 offset0:88 offset1:89
	v_mul_f32_e32 v132, v106, v130
	v_mul_f32_e32 v134, v107, v130
	v_mul_f32_e32 v133, v42, v131
	ds_write2st64_b32 v214, v132, v134 offset0:26 offset1:27
	v_mul_f32_e32 v132, v43, v131
	ds_write2st64_b32 v214, v133, v132 offset0:90 offset1:91
	v_mul_f32_e32 v132, v108, v130
	v_mul_f32_e32 v134, v109, v130
	v_mul_f32_e32 v133, v44, v131
	ds_write2st64_b32 v214, v132, v134 offset0:28 offset1:29
	v_mul_f32_e32 v132, v45, v131
	ds_write2st64_b32 v214, v133, v132 offset0:92 offset1:93
	v_mul_f32_e32 v132, v110, v130
	v_mul_f32_e32 v134, v111, v130
	v_mul_f32_e32 v133, v46, v131
	ds_write2st64_b32 v214, v132, v134 offset0:30 offset1:31
	v_mul_f32_e32 v132, v47, v131
	ds_write2st64_b32 v214, v133, v132 offset0:94 offset1:95
	v_mul_f32_e32 v132, v80, v130
	v_mul_f32_e32 v134, v81, v130
	v_mul_f32_e32 v133, v16, v131
	ds_write2st64_b32 v214, v132, v134 offset0:32 offset1:33
	v_mul_f32_e32 v132, v17, v131
	ds_write2st64_b32 v214, v133, v132 offset0:96 offset1:97
	v_mul_f32_e32 v132, v82, v130
	v_mul_f32_e32 v134, v83, v130
	v_mul_f32_e32 v133, v18, v131
	ds_write2st64_b32 v214, v132, v134 offset0:34 offset1:35
	v_mul_f32_e32 v132, v19, v131
	ds_write2st64_b32 v214, v133, v132 offset0:98 offset1:99
	v_mul_f32_e32 v132, v84, v130
	v_mul_f32_e32 v134, v85, v130
	v_mul_f32_e32 v133, v20, v131
	ds_write2st64_b32 v214, v132, v134 offset0:36 offset1:37
	v_mul_f32_e32 v132, v21, v131
	ds_write2st64_b32 v214, v133, v132 offset0:100 offset1:101
	v_mul_f32_e32 v132, v86, v130
	v_mul_f32_e32 v134, v87, v130
	v_mul_f32_e32 v133, v22, v131
	ds_write2st64_b32 v214, v132, v134 offset0:38 offset1:39
	v_mul_f32_e32 v132, v23, v131
	ds_write2st64_b32 v214, v133, v132 offset0:102 offset1:103
	v_mul_f32_e32 v132, v88, v130
	v_mul_f32_e32 v134, v89, v130
	v_mul_f32_e32 v133, v24, v131
	ds_write2st64_b32 v214, v132, v134 offset0:40 offset1:41
	v_mul_f32_e32 v132, v25, v131
	ds_write2st64_b32 v214, v133, v132 offset0:104 offset1:105
	v_mul_f32_e32 v132, v90, v130
	v_mul_f32_e32 v134, v91, v130
	v_mul_f32_e32 v133, v26, v131
	ds_write2st64_b32 v214, v132, v134 offset0:42 offset1:43
	v_mul_f32_e32 v132, v27, v131
	ds_write2st64_b32 v214, v133, v132 offset0:106 offset1:107
	v_mul_f32_e32 v132, v92, v130
	v_mul_f32_e32 v134, v93, v130
	v_mul_f32_e32 v133, v28, v131
	ds_write2st64_b32 v214, v132, v134 offset0:44 offset1:45
	v_mul_f32_e32 v132, v29, v131
	ds_write2st64_b32 v214, v133, v132 offset0:108 offset1:109
	v_mul_f32_e32 v132, v94, v130
	v_mul_f32_e32 v134, v95, v130
	v_mul_f32_e32 v133, v30, v131
	ds_write2st64_b32 v214, v132, v134 offset0:46 offset1:47
	v_mul_f32_e32 v132, v31, v131
	ds_write2st64_b32 v214, v133, v132 offset0:110 offset1:111
	v_mul_f32_e32 v132, v64, v130
	v_mul_f32_e32 v134, v65, v130
	v_mul_f32_e32 v133, v0, v131
	ds_write2st64_b32 v214, v132, v134 offset0:48 offset1:49
	v_mul_f32_e32 v132, v1, v131
	ds_write2st64_b32 v214, v133, v132 offset0:112 offset1:113
	v_mul_f32_e32 v132, v66, v130
	v_mul_f32_e32 v134, v67, v130
	v_mul_f32_e32 v133, v2, v131
	ds_write2st64_b32 v214, v132, v134 offset0:50 offset1:51
	v_mul_f32_e32 v132, v3, v131
	ds_write2st64_b32 v214, v133, v132 offset0:114 offset1:115
	v_mul_f32_e32 v132, v68, v130
	v_mul_f32_e32 v134, v69, v130
	v_mul_f32_e32 v133, v4, v131
	ds_write2st64_b32 v214, v132, v134 offset0:52 offset1:53
	v_mul_f32_e32 v132, v5, v131
	ds_write2st64_b32 v214, v133, v132 offset0:116 offset1:117
	v_mul_f32_e32 v132, v70, v130
	v_mul_f32_e32 v134, v71, v130
	v_mul_f32_e32 v133, v6, v131
	ds_write2st64_b32 v214, v132, v134 offset0:54 offset1:55
	v_mul_f32_e32 v132, v7, v131
	ds_write2st64_b32 v214, v133, v132 offset0:118 offset1:119
	v_mul_f32_e32 v132, v72, v130
	v_mul_f32_e32 v134, v73, v130
	v_mul_f32_e32 v133, v8, v131
	ds_write2st64_b32 v214, v132, v134 offset0:56 offset1:57
	v_mul_f32_e32 v132, v9, v131
	ds_write2st64_b32 v214, v133, v132 offset0:120 offset1:121
	v_mul_f32_e32 v132, v74, v130
	v_mul_f32_e32 v134, v75, v130
	v_mul_f32_e32 v133, v10, v131
	ds_write2st64_b32 v214, v132, v134 offset0:58 offset1:59
	v_mul_f32_e32 v132, v11, v131
	ds_write2st64_b32 v214, v133, v132 offset0:122 offset1:123
	v_mul_f32_e32 v132, v76, v130
	v_mul_f32_e32 v134, v77, v130
	v_mul_f32_e32 v133, v12, v131
	ds_write2st64_b32 v214, v132, v134 offset0:60 offset1:61
	v_mul_f32_e32 v132, v13, v131
	ds_write2st64_b32 v214, v133, v132 offset0:124 offset1:125
	v_mul_f32_e32 v132, v78, v130
	v_mul_f32_e32 v130, v79, v130
	v_mul_f32_e32 v133, v14, v131
	ds_write2st64_b32 v214, v132, v130 offset0:62 offset1:63
	v_mul_f32_e32 v130, v15, v131
	ds_write2st64_b32 v214, v133, v130 offset0:126 offset1:127
